# attention body: alternate s_setprio between the two wave groups every 6 MFMA gaps to balance SIMD partners
# baseline (speedup 1.0000x reference)
.Lfa_p2:
	s_waitcnt lgkmcnt(8)
	v_mfma_f32_32x32x16_bf16 v[96:111], v[160:163], v[128:131], v[80:95]
	ds_read_b128 v[160:163], v3 offset:16384
	s_xor_b32 s11, s10, 0x8000
	s_add_i32 s11, s11, s24
	s_sub_i32 s16, s8, 64
	s_mov_b32 s17, 0
	s_lshl_b64 s[16:17], s[16:17], 11
	s_mov_b32 m0, s11
	v_lshl_add_u64 v[10:11], v[144:145], 0, s[16:17]
	global_load_lds_dwordx4 v[10:11], off
	v_mfma_f32_32x32x16_bf16 v[112:127], v[164:167], v[128:131], v[80:95]
	ds_read_b128 v[164:167], v3 offset:24576
	v_add_u32_e32 v0, s9, v157
	v_add_u32_e32 v0, 0x10000, v0
	v_add_u32_e32 v6, v0, v149
	s_add_i32 m0, s11, 0x2000
	v_lshl_add_u64 v[10:11], v[10:11], 0, s[60:61]
	global_load_lds_dwordx4 v[10:11], off
	s_waitcnt lgkmcnt(8)
	v_mfma_f32_32x32x16_bf16 v[96:111], v[168:171], v[132:135], v[96:111]
	ds_read_b128 v[168:171], v4 offset:16384
	v_add_u32_e32 v7, v0, v151
	v_add_u32_e32 v8, v0, v153
	v_add_u32_e32 v9, v0, v155
	v_lshl_add_u64 v[12:13], v[146:147], 0, s[6:7]
	s_mov_b64 s[16:17], 0x6d08000
	s_add_i32 m0, s11, 0x10000
	v_lshl_add_u64 v[10:11], v[12:13], 0, s[16:17]
	global_load_lds_dwordx4 v[10:11], off
	v_mfma_f32_32x32x16_bf16 v[112:127], v[224:227], v[132:135], v[112:127]
	ds_read_b128 v[224:227], v4 offset:24576
	s_mov_b64 s[16:17], 0x6d0a000
	s_add_i32 m0, s11, 0x12000
	v_lshl_add_u64 v[10:11], v[12:13], 0, s[16:17]
	global_load_lds_dwordx4 v[10:11], off
	s_waitcnt lgkmcnt(8)
	v_mfma_f32_32x32x16_bf16 v[96:111], v[228:231], v[136:139], v[96:111]
	ds_read_b128 v[228:231], v5 offset:16384
	s_mov_b32 s16, s8
	s_mov_b32 s17, 0
	s_lshl_b64 s[16:17], s[16:17], 11
	s_add_i32 m0, s11, 0x4000
	v_lshl_add_u64 v[10:11], v[144:145], 0, s[16:17]
	global_load_lds_dwordx4 v[10:11], off
	v_mfma_f32_32x32x16_bf16 v[112:127], v[232:235], v[136:139], v[112:127]
	ds_read_b128 v[232:235], v5 offset:24576
	s_add_i32 m0, s11, 0x6000
	v_lshl_add_u64 v[10:11], v[10:11], 0, s[60:61]
	global_load_lds_dwordx4 v[10:11], off
	s_cmp_ge_u32 s24, 0x1000
	s_cbranch_scc1 .Lfa_pa1
	s_setprio 0
.Lfa_pa1:
	s_waitcnt lgkmcnt(8)
	v_mfma_f32_32x32x16_bf16 v[96:111], v[236:239], v[140:143], v[96:111]
	ds_read_b128 v[236:239], v6
	s_mov_b64 s[16:17], 0x6d0c000
	s_add_i32 m0, s11, 0x14000
	v_lshl_add_u64 v[10:11], v[12:13], 0, s[16:17]
	global_load_lds_dwordx4 v[10:11], off
	v_mfma_f32_32x32x16_bf16 v[112:127], v[244:247], v[140:143], v[112:127]
	ds_read_b128 v[244:247], v6 offset:4096
	s_mov_b64 s[16:17], 0x6d0e000
	s_add_i32 m0, s11, 0x16000
	v_lshl_add_u64 v[10:11], v[12:13], 0, s[16:17]
	global_load_lds_dwordx4 v[10:11], off
	s_waitcnt lgkmcnt(8)
	v_mfma_f32_32x32x16_bf16 v[192:207], v[248:251], v[128:131], v[80:95]
	ds_read_b128 v[248:251], v6 offset:8192
	v_max3_f32 v190, v96, v97, v98
	v_max3_f32 v190, v190, v99, v100
	v_max3_f32 v190, v190, v101, v102
	v_max3_f32 v190, v190, v103, v104
	v_mfma_f32_32x32x16_bf16 v[208:223], v[252:255], v[128:131], v[80:95]
	ds_read_b128 v[252:255], v6 offset:12288
	v_max3_f32 v190, v190, v105, v106
	v_max3_f32 v190, v190, v107, v108
	v_max3_f32 v190, v190, v109, v110
	v_max3_f32 v190, v190, v111, v111
	v_max3_f32 v191, v112, v113, v114
	v_max3_f32 v191, v191, v115, v116
	s_waitcnt lgkmcnt(8)
	v_mfma_f32_32x32x16_bf16 v[192:207], v[160:163], v[132:135], v[192:207]
	ds_read_b128 v[160:163], v7
	v_max3_f32 v191, v191, v117, v118
	v_max3_f32 v191, v191, v119, v120
	v_max3_f32 v191, v191, v121, v122
	v_max3_f32 v191, v191, v123, v124
	v_max3_f32 v191, v191, v125, v126
	v_max3_f32 v191, v191, v127, v127
	v_mfma_f32_32x32x16_bf16 v[208:223], v[164:167], v[132:135], v[208:223]
	ds_read_b128 v[164:167], v7 offset:4096
	v_max_f32_e32 v0, v190, v191
	v_mov_b32_e32 v15, v0
	s_nop 1
	v_permlane32_swap_b32_e32 v0, v15
	v_max_f32_e32 v0, v0, v15
	s_nop 0
	v_cmp_lt_f32_e32 vcc, s67, v0
	s_cbranch_vccnz .Lfa_rareA
.Lfa_retA:
	s_cmp_ge_u32 s24, 0x1000
	s_cbranch_scc1 .Lfa_pa2
	s_setprio 2
.Lfa_pa2:
	s_waitcnt lgkmcnt(8)
	v_mfma_f32_32x32x16_bf16 v[192:207], v[168:171], v[136:139], v[192:207]
	ds_read_b128 v[168:171], v7 offset:8192
	v_exp_f32_e32 v96, v96
	v_exp_f32_e32 v97, v97
	v_exp_f32_e32 v98, v98
	v_exp_f32_e32 v99, v99
	v_exp_f32_e32 v100, v100
	v_mfma_f32_32x32x16_bf16 v[208:223], v[224:227], v[136:139], v[208:223]
	ds_read_b128 v[224:227], v7 offset:12288
	v_exp_f32_e32 v101, v101
	v_exp_f32_e32 v102, v102
	v_exp_f32_e32 v103, v103
	v_add_f32_e32 v159, v159, v96
	v_add_f32_e32 v159, v159, v97
	s_waitcnt lgkmcnt(8)
	v_mfma_f32_32x32x16_bf16 v[192:207], v[228:231], v[140:143], v[192:207]
	ds_read_b128 v[228:231], v8
	v_add_f32_e32 v159, v159, v98
	v_add_f32_e32 v159, v159, v99
	v_cvt_pk_bf16_f32 v96, v96, v97
	v_cvt_pk_bf16_f32 v97, v98, v99
	v_add_f32_e32 v159, v159, v100
	v_mfma_f32_32x32x16_bf16 v[208:223], v[232:235], v[140:143], v[208:223]
	ds_read_b128 v[232:235], v8 offset:4096
	v_add_f32_e32 v159, v159, v101
	v_cvt_pk_bf16_f32 v98, v100, v101
	v_cvt_pk_bf16_f32 v99, v102, v103
	v_add_f32_e32 v159, v159, v102
	v_add_f32_e32 v159, v159, v103
	s_waitcnt lgkmcnt(8)
	v_mfma_f32_32x32x16_bf16 v[64:79], v[236:239], v[96:99], v[64:79]
	ds_read_b128 v[236:239], v8 offset:8192
	v_exp_f32_e32 v104, v104
	v_exp_f32_e32 v105, v105
	v_exp_f32_e32 v106, v106
	v_exp_f32_e32 v107, v107
	v_exp_f32_e32 v108, v108
	v_mfma_f32_32x32x16_bf16 v[48:63], v[244:247], v[96:99], v[48:63]
	ds_read_b128 v[244:247], v8 offset:12288
	v_exp_f32_e32 v109, v109
	v_exp_f32_e32 v110, v110
	v_exp_f32_e32 v111, v111
	v_add_f32_e32 v159, v159, v104
	v_add_f32_e32 v159, v159, v105
	s_cmp_ge_u32 s24, 0x1000
	s_cbranch_scc1 .Lfa_pa3
	s_setprio 0
.Lfa_pa3:
	s_waitcnt lgkmcnt(8)
	v_mfma_f32_32x32x16_bf16 v[32:47], v[248:251], v[96:99], v[32:47]
	ds_read_b128 v[248:251], v9
	v_add_f32_e32 v159, v159, v106
	v_add_f32_e32 v159, v159, v107
	v_cvt_pk_bf16_f32 v104, v104, v105
	v_cvt_pk_bf16_f32 v105, v106, v107
	v_add_f32_e32 v159, v159, v108
	v_mfma_f32_32x32x16_bf16 v[16:31], v[252:255], v[96:99], v[16:31]
	ds_read_b128 v[252:255], v9 offset:4096
	v_add_f32_e32 v159, v159, v109
	v_cvt_pk_bf16_f32 v106, v108, v109
	v_cvt_pk_bf16_f32 v107, v110, v111
	v_add_f32_e32 v159, v159, v110
	v_add_f32_e32 v159, v159, v111
	s_waitcnt lgkmcnt(8)
	v_mfma_f32_32x32x16_bf16 v[64:79], v[160:163], v[104:107], v[64:79]
	ds_read_b128 v[160:163], v9 offset:8192
	v_exp_f32_e32 v112, v112
	v_exp_f32_e32 v113, v113
	v_exp_f32_e32 v114, v114
	v_exp_f32_e32 v115, v115
	v_exp_f32_e32 v116, v116
	v_mfma_f32_32x32x16_bf16 v[48:63], v[164:167], v[104:107], v[48:63]
	ds_read_b128 v[164:167], v9 offset:12288
	v_exp_f32_e32 v117, v117
	v_exp_f32_e32 v118, v118
	v_exp_f32_e32 v119, v119
	v_add_f32_e32 v159, v159, v112
	v_add_f32_e32 v159, v159, v113
	s_waitcnt lgkmcnt(8)
	v_mfma_f32_32x32x16_bf16 v[32:47], v[168:171], v[104:107], v[32:47]
	ds_read_b128 v[168:171], v6 offset:16384
	v_add_f32_e32 v159, v159, v114
	v_add_f32_e32 v159, v159, v115
	v_cvt_pk_bf16_f32 v112, v112, v113
	v_cvt_pk_bf16_f32 v113, v114, v115
	v_add_f32_e32 v159, v159, v116
	v_mfma_f32_32x32x16_bf16 v[16:31], v[224:227], v[104:107], v[16:31]
	ds_read_b128 v[224:227], v6 offset:20480
	v_add_f32_e32 v159, v159, v117
	v_cvt_pk_bf16_f32 v114, v116, v117
	v_cvt_pk_bf16_f32 v115, v118, v119
	v_add_f32_e32 v159, v159, v118
	v_add_f32_e32 v159, v159, v119
	s_cmp_ge_u32 s24, 0x1000
	s_cbranch_scc1 .Lfa_pa4
	s_setprio 2
.Lfa_pa4:
	s_waitcnt lgkmcnt(8)
	v_mfma_f32_32x32x16_bf16 v[64:79], v[228:231], v[112:115], v[64:79]
	ds_read_b128 v[228:231], v6 offset:24576
	v_exp_f32_e32 v120, v120
	v_exp_f32_e32 v121, v121
	v_exp_f32_e32 v122, v122
	v_exp_f32_e32 v123, v123
	v_exp_f32_e32 v124, v124
	v_max3_f32 v190, v192, v193, v194
	v_max3_f32 v190, v190, v195, v196
	v_max3_f32 v190, v190, v197, v198
	v_max3_f32 v190, v190, v199, v200
	v_mfma_f32_32x32x16_bf16 v[48:63], v[232:235], v[112:115], v[48:63]
	ds_read_b128 v[232:235], v6 offset:28672
	v_exp_f32_e32 v125, v125
	v_exp_f32_e32 v126, v126
	v_exp_f32_e32 v127, v127
	v_add_f32_e32 v159, v159, v120
	v_add_f32_e32 v159, v159, v121
	v_max3_f32 v190, v190, v201, v202
	v_max3_f32 v190, v190, v203, v204
	v_max3_f32 v190, v190, v205, v206
	v_max3_f32 v190, v190, v207, v207
	s_waitcnt lgkmcnt(8)
	v_mfma_f32_32x32x16_bf16 v[32:47], v[236:239], v[112:115], v[32:47]
	ds_read_b128 v[236:239], v7 offset:16384
	v_add_f32_e32 v159, v159, v122
	v_add_f32_e32 v159, v159, v123
	v_cvt_pk_bf16_f32 v120, v120, v121
	v_cvt_pk_bf16_f32 v121, v122, v123
	v_add_f32_e32 v159, v159, v124
	v_max3_f32 v191, v208, v209, v210
	v_max3_f32 v191, v191, v211, v212
	v_max3_f32 v191, v191, v213, v214
	v_max3_f32 v191, v191, v215, v216
	v_mfma_f32_32x32x16_bf16 v[16:31], v[244:247], v[112:115], v[16:31]
	ds_read_b128 v[244:247], v7 offset:20480
	v_add_f32_e32 v159, v159, v125
	v_cvt_pk_bf16_f32 v122, v124, v125
	v_cvt_pk_bf16_f32 v123, v126, v127
	v_add_f32_e32 v159, v159, v126
	v_add_f32_e32 v159, v159, v127
	v_max3_f32 v191, v191, v217, v218
	v_max3_f32 v191, v191, v219, v220
	v_max3_f32 v191, v191, v221, v222
	v_max3_f32 v191, v191, v223, v223
	s_waitcnt lgkmcnt(8)
	v_mfma_f32_32x32x16_bf16 v[64:79], v[248:251], v[120:123], v[64:79]
	ds_read_b128 v[248:251], v7 offset:24576
	v_max_f32_e32 v0, v190, v191
	v_mov_b32_e32 v15, v0
	s_nop 1
	v_permlane32_swap_b32_e32 v0, v15
	v_max_f32_e32 v0, v0, v15
	s_nop 0
	v_cmp_lt_f32_e32 vcc, s67, v0
	s_or_b64 vcc, vcc, s[18:19]
	s_cbranch_vccnz .Lfa_rareB
.Lfa_retB:
	v_exp_f32_e32 v192, v192
	v_exp_f32_e32 v193, v193
	v_exp_f32_e32 v194, v194
	v_exp_f32_e32 v195, v195
	v_exp_f32_e32 v196, v196
	v_mfma_f32_32x32x16_bf16 v[48:63], v[252:255], v[120:123], v[48:63]
	ds_read_b128 v[252:255], v7 offset:28672
	v_exp_f32_e32 v197, v197
	v_exp_f32_e32 v198, v198
	v_exp_f32_e32 v199, v199
	v_add_f32_e32 v159, v159, v192
	v_add_f32_e32 v159, v159, v193
	s_cmp_ge_u32 s24, 0x1000
	s_cbranch_scc1 .Lfa_pa5
	s_setprio 0
.Lfa_pa5:
	s_waitcnt lgkmcnt(8)
	v_mfma_f32_32x32x16_bf16 v[32:47], v[160:163], v[120:123], v[32:47]
	ds_read_b128 v[160:163], v8 offset:16384
	v_add_f32_e32 v159, v159, v194
	v_add_f32_e32 v159, v159, v195
	v_cvt_pk_bf16_f32 v192, v192, v193
	v_cvt_pk_bf16_f32 v193, v194, v195
	v_add_f32_e32 v159, v159, v196
	v_mfma_f32_32x32x16_bf16 v[16:31], v[164:167], v[120:123], v[16:31]
	ds_read_b128 v[164:167], v8 offset:20480
	v_add_f32_e32 v159, v159, v197
	v_cvt_pk_bf16_f32 v194, v196, v197
	v_cvt_pk_bf16_f32 v195, v198, v199
	v_add_f32_e32 v159, v159, v198
	v_add_f32_e32 v159, v159, v199
	s_cmp_lg_u32 s80, 0
	s_cbranch_scc1 .Lfa_fixO
.Lfa_retO:
	s_waitcnt lgkmcnt(8)
	v_mfma_f32_32x32x16_bf16 v[64:79], v[168:171], v[192:195], v[64:79]
	ds_read_b128 v[168:171], v8 offset:24576
	v_exp_f32_e32 v200, v200
	v_exp_f32_e32 v201, v201
	v_exp_f32_e32 v202, v202
	v_exp_f32_e32 v203, v203
	v_exp_f32_e32 v204, v204
	v_mfma_f32_32x32x16_bf16 v[48:63], v[224:227], v[192:195], v[48:63]
	ds_read_b128 v[224:227], v8 offset:28672
	v_exp_f32_e32 v205, v205
	v_exp_f32_e32 v206, v206
	v_exp_f32_e32 v207, v207
	v_add_f32_e32 v159, v159, v200
	v_add_f32_e32 v159, v159, v201
	s_waitcnt lgkmcnt(8)
	v_mfma_f32_32x32x16_bf16 v[32:47], v[228:231], v[192:195], v[32:47]
	ds_read_b128 v[228:231], v9 offset:16384
	v_add_f32_e32 v159, v159, v202
	v_add_f32_e32 v159, v159, v203
	v_cvt_pk_bf16_f32 v200, v200, v201
	v_cvt_pk_bf16_f32 v201, v202, v203
	v_add_f32_e32 v159, v159, v204
	v_mfma_f32_32x32x16_bf16 v[16:31], v[232:235], v[192:195], v[16:31]
	ds_read_b128 v[232:235], v9 offset:20480
	v_add_f32_e32 v159, v159, v205
	v_cvt_pk_bf16_f32 v202, v204, v205
	v_cvt_pk_bf16_f32 v203, v206, v207
	v_add_f32_e32 v159, v159, v206
	v_add_f32_e32 v159, v159, v207
	s_cmp_ge_u32 s24, 0x1000
	s_cbranch_scc1 .Lfa_pa6
	s_setprio 2
.Lfa_pa6:
	s_waitcnt lgkmcnt(8)
	v_mfma_f32_32x32x16_bf16 v[64:79], v[236:239], v[200:203], v[64:79]
	ds_read_b128 v[236:239], v9 offset:24576
	v_exp_f32_e32 v208, v208
	v_exp_f32_e32 v209, v209
	v_exp_f32_e32 v210, v210
	v_exp_f32_e32 v211, v211
	v_exp_f32_e32 v212, v212
	v_mfma_f32_32x32x16_bf16 v[48:63], v[244:247], v[200:203], v[48:63]
	ds_read_b128 v[244:247], v9 offset:28672
	v_exp_f32_e32 v213, v213
	v_exp_f32_e32 v214, v214
	v_exp_f32_e32 v215, v215
	v_add_f32_e32 v159, v159, v208
	v_add_f32_e32 v159, v159, v209
	s_waitcnt lgkmcnt(8)
	v_mfma_f32_32x32x16_bf16 v[32:47], v[248:251], v[200:203], v[32:47]
	v_add_f32_e32 v159, v159, v210
	v_add_f32_e32 v159, v159, v211
	v_cvt_pk_bf16_f32 v208, v208, v209
	v_cvt_pk_bf16_f32 v209, v210, v211
	v_add_f32_e32 v159, v159, v212
	v_mfma_f32_32x32x16_bf16 v[16:31], v[252:255], v[200:203], v[16:31]
	v_add_f32_e32 v159, v159, v213
	v_cvt_pk_bf16_f32 v210, v212, v213
	v_cvt_pk_bf16_f32 v211, v214, v215
	v_add_f32_e32 v159, v159, v214
	v_add_f32_e32 v159, v159, v215
	s_waitcnt lgkmcnt(6)
	v_mfma_f32_32x32x16_bf16 v[64:79], v[160:163], v[208:211], v[64:79]
	v_exp_f32_e32 v216, v216
	v_exp_f32_e32 v217, v217
	v_exp_f32_e32 v218, v218
	v_exp_f32_e32 v219, v219
	v_exp_f32_e32 v220, v220
	v_mfma_f32_32x32x16_bf16 v[48:63], v[164:167], v[208:211], v[48:63]
	v_exp_f32_e32 v221, v221
	v_exp_f32_e32 v222, v222
	v_exp_f32_e32 v223, v223
	v_add_f32_e32 v159, v159, v216
	v_add_f32_e32 v159, v159, v217
	s_cmp_ge_u32 s24, 0x1000
	s_cbranch_scc1 .Lfa_pa7
	s_setprio 0
.Lfa_pa7:
	s_waitcnt lgkmcnt(4)
	v_mfma_f32_32x32x16_bf16 v[32:47], v[168:171], v[208:211], v[32:47]
	v_add_f32_e32 v159, v159, v218
	v_add_f32_e32 v159, v159, v219
	v_cvt_pk_bf16_f32 v216, v216, v217
	v_cvt_pk_bf16_f32 v217, v218, v219
	v_add_f32_e32 v159, v159, v220
	v_mfma_f32_32x32x16_bf16 v[16:31], v[224:227], v[208:211], v[16:31]
	v_add_f32_e32 v159, v159, v221
	v_cvt_pk_bf16_f32 v218, v220, v221
	v_cvt_pk_bf16_f32 v219, v222, v223
	v_add_f32_e32 v159, v159, v222
	v_add_f32_e32 v159, v159, v223
	s_waitcnt lgkmcnt(2)
	v_mfma_f32_32x32x16_bf16 v[64:79], v[228:231], v[216:219], v[64:79]
	s_add_i32 s26, s26, 1
	s_add_u32 s6, s6, 0x8000
	v_mfma_f32_32x32x16_bf16 v[48:63], v[232:235], v[216:219], v[48:63]
	s_addc_u32 s7, s7, 0
	s_addk_i32 s8, 0x80
	s_waitcnt lgkmcnt(0)
	v_mfma_f32_32x32x16_bf16 v[32:47], v[236:239], v[216:219], v[32:47]
	v_add_u32_e32 v158, 0xffffff80, v158
	v_mfma_f32_32x32x16_bf16 v[16:31], v[244:247], v[216:219], v[16:31]
	s_setprio 0
	s_branch .LBB0_205
